# MLA attention item prologue: the thread's four Q-tile loads issued together (was a 4-trip load->vmcnt(0)->ds_write loop)
# speedup vs baseline: 1.0034x; 1.0034x over previous
; #define LAS __attribute__((address_space(3)))
; template <bool MLA>
; __device__ __forceinline__ void attn_phase(const Args& a, LAS unsigned char* lds) {
;     ...
;         if (MLA) {
;             for (int idx = tid; idx < 256 * 8; idx += NTHREADS) { const int lr = idx >> 3, ch = idx & 7; const int rr = lr < nq ? lr : 0;
;                 *(LAS u32x4*)(Qs + lr * QST + ch * 8) = *(const u32x4*)(Qg + (qrow0 + rr) * 1536 + h * 96 + ch * 8); }
.LBB0_446:
	s_and_b32 s64, s33, 15
	s_mul_i32 s8, s64, 0x60
	s_barrier
	s_and_saveexec_b64 s[0:1], s[36:37]
	v_readlane_b32 s12, v253, 50
	v_readlane_b32 s13, v253, 51
	s_movk_i32 s9, 0xc00
	s_movk_i32 s14, 0xd0
	s_movk_i32 s15, 0x5ff
	s_cbranch_execz .LBB0_449
	s_lshl_b32 s2, s8, 1
	v_readlane_b32 s4, v253, 20
	v_readlane_b32 s5, v253, 21
	s_add_u32 s2, s4, s2
	s_addc_u32 s3, s5, 0
	s_mov_b64 s[4:5], 0
	v_mov_b32_e32 v2, v157
	v_mov_b32_e32 v3, v107
	v_lshlrev_b32_e32 v0, 1, v157
	s_waitcnt lgkmcnt(0)
	v_and_b32_e32 v0, 0x70, v0
	v_ashrrev_i32_e32 v2, 3, v107
	v_add_u32_e32 v32, 0, v2
	v_cmp_gt_i32_e32 vcc, s62, v32
	v_mov_b64_e32 v[208:209], s[2:3]
	v_mul_lo_u32 v33, v32, s14
	v_add3_u32 v232, 0, v33, v0
	v_cndmask_b32_e32 v30, 0, v32, vcc
	v_ashrrev_i32_e32 v31, 31, v30
	v_lshl_add_u64 v[30:31], v[30:31], 0, s[12:13]
	v_mad_u64_u32 v[208:209], s[10:11], v30, s9, v[208:209]
	v_mad_i32_i24 v209, v31, s9, v209
	v_lshl_add_u64 v[208:209], v[208:209], 0, v[0:1]
	global_load_dwordx4 v[216:219], v[208:209], off
	v_add_u32_e32 v32, 64, v2
	v_cmp_gt_i32_e32 vcc, s62, v32
	v_mov_b64_e32 v[210:211], s[2:3]
	v_mul_lo_u32 v33, v32, s14
	v_add3_u32 v233, 0, v33, v0
	v_cndmask_b32_e32 v30, 0, v32, vcc
	v_ashrrev_i32_e32 v31, 31, v30
	v_lshl_add_u64 v[30:31], v[30:31], 0, s[12:13]
	v_mad_u64_u32 v[210:211], s[10:11], v30, s9, v[210:211]
	v_mad_i32_i24 v211, v31, s9, v211
	v_lshl_add_u64 v[210:211], v[210:211], 0, v[0:1]
	global_load_dwordx4 v[220:223], v[210:211], off
	v_add_u32_e32 v32, 128, v2
	v_cmp_gt_i32_e32 vcc, s62, v32
	v_mov_b64_e32 v[212:213], s[2:3]
	v_mul_lo_u32 v33, v32, s14
	v_add3_u32 v239, 0, v33, v0
	v_cndmask_b32_e32 v30, 0, v32, vcc
	v_ashrrev_i32_e32 v31, 31, v30
	v_lshl_add_u64 v[30:31], v[30:31], 0, s[12:13]
	v_mad_u64_u32 v[212:213], s[10:11], v30, s9, v[212:213]
	v_mad_i32_i24 v213, v31, s9, v213
	v_lshl_add_u64 v[212:213], v[212:213], 0, v[0:1]
	global_load_dwordx4 v[224:227], v[212:213], off
	v_add_u32_e32 v32, 192, v2
	v_cmp_gt_i32_e32 vcc, s62, v32
	v_mov_b64_e32 v[214:215], s[2:3]
	v_mul_lo_u32 v33, v32, s14
	v_add3_u32 v240, 0, v33, v0
	v_cndmask_b32_e32 v30, 0, v32, vcc
	v_ashrrev_i32_e32 v31, 31, v30
	v_lshl_add_u64 v[30:31], v[30:31], 0, s[12:13]
	v_mad_u64_u32 v[214:215], s[10:11], v30, s9, v[214:215]
	v_mad_i32_i24 v215, v31, s9, v215
	v_lshl_add_u64 v[214:215], v[214:215], 0, v[0:1]
	global_load_dwordx4 v[228:231], v[214:215], off
	s_waitcnt vmcnt(0)
	ds_write_b128 v232, v[216:219]
	ds_write_b128 v233, v[220:223]
	ds_write_b128 v239, v[224:227]
	ds_write_b128 v240, v[228:231]
